# GEMM phase prologue: issue K-tile 1 staging loads together with K-tile 0 (one exposed round trip instead of two)
# baseline (speedup 1.0000x reference)
.LBB0_182:
	s_lshl_b64 s[28:29], s[10:11], 19
	s_and_b64 s[38:39], s[4:5], exec
	v_readlane_b32 s10, v252, 54
	v_readlane_b32 s31, v252, 56
	s_cselect_b32 s10, s31, s10
	v_readlane_b32 s31, v252, 53
	v_readlane_b32 s38, v252, 55
	s_cselect_b32 s31, s38, s31
	s_add_u32 s28, s31, s28
	s_addc_u32 s29, s10, s29
	v_lshl_add_u64 v[8:9], v[0:1], 0, s[18:19]
	s_add_i32 m0, s45, 0x18000
	global_load_lds_dwordx4 v[8:9], off
	v_lshl_add_u64 v[8:9], v[0:1], 0, s[20:21]
	s_add_i32 m0, s45, 0x1a000
	s_add_i32 s10, s45, 0x8000
	global_load_lds_dwordx4 v[8:9], off
	v_lshl_add_u64 v[8:9], v[2:3], 0, s[18:19]
	s_mov_b32 m0, s10
	s_add_i32 s74, s45, 0xa000
	global_load_lds_dwordx4 v[8:9], off
	v_lshl_add_u64 v[2:3], v[2:3], 0, s[20:21]
	s_mov_b32 m0, s74
	s_sext_i32_i8 s77, s0
	global_load_lds_dwordx4 v[2:3], off
	v_lshl_add_u64 v[2:3], v[0:1], 0, s[22:23]
	s_add_i32 m0, s45, 0x1c000
	v_lshl_add_u64 v[0:1], v[0:1], 0, s[24:25]
	global_load_lds_dwordx4 v[2:3], off
	s_add_i32 m0, s45, 0x1e000
	s_lshl_b32 s0, s37, 13
	global_load_lds_dwordx4 v[0:1], off
	s_waitcnt vmcnt(8)
	s_barrier
	v_lshrrev_b32_e32 v1, 1, v4
	v_and_b32_e32 v1, 24, v1
	v_and_b32_e32 v0, 15, v4
	v_lshlrev_b32_e32 v2, 1, v1
	v_lshl_or_b32 v145, s37, 6, v0
	v_lshl_or_b32 v2, v0, 6, v2
	v_lshlrev_b32_e32 v0, 2, v0
	v_and_b32_e32 v3, 32, v0
	v_bitop3_b32 v8, v2, s0, v3 bitop3:0xde
	s_lshl_b32 s0, s1, 5
	s_and_b32 s38, s0, 0x60
	s_lshl_b32 s0, s38, 7
	s_cmpk_lt_u32 s30, 0x100
	s_cselect_b64 s[30:31], -1, 0
	v_readlane_b32 s39, v252, 57
	s_lshl_b32 s37, s37, 8
	s_add_i32 s37, s39, s37
	v_add_u32_e32 v148, s37, v0
	v_lshlrev_b32_e32 v0, 14, v5
	v_and_b32_e32 v0, 0xffff8000, v0
	s_waitcnt vmcnt(6)
	v_or_b32_e32 v149, s38, v1
	v_lshl_add_u32 v0, v6, 11, v0
	v_and_b32_e32 v1, 1, v5
	v_bitop3_b32 v146, v2, s0, v3 bitop3:0xde
	s_movk_i32 s0, 0x100
	s_mov_b32 s37, s11
	s_and_b64 s[4:5], s[4:5], exec
	v_lshl_or_b32 v0, v1, 6, v0
	v_cmp_gt_i32_e64 s[0:1], s0, v4
	v_lshl_add_u32 v147, v4, 2, s39
	s_cselect_b32 s75, 8, 10
	s_mov_b32 s76, 0
	v_lshl_add_u32 v132, v7, 1, v0
	v_mov_b32_e32 v133, v129
	v_add_u32_e32 v150, 0, v8
	v_mov_b64_e32 v[134:135], s[36:37]
	s_barrier
	s_branch .LBB0_185

.LBB0_223:
	v_lshrrev_b32_e32 v9, 1, v4
	v_and_b32_e32 v8, 15, v4
	v_and_b32_e32 v10, 24, v9
	v_lshlrev_b32_e32 v9, 1, v10
	v_lshlrev_b32_e32 v11, 2, v8
	v_lshl_or_b32 v140, s31, 6, v8
	v_lshl_or_b32 v9, v8, 6, v9
	s_lshl_b32 s18, s31, 13
	v_and_b32_e32 v8, 32, v11
	v_bitop3_b32 v12, v9, s18, v8 bitop3:0xde
	s_lshl_b32 s18, s29, 5
	s_and_b32 s18, s18, 0x60
	s_lshl_b32 s21, s18, 7
	v_bitop3_b32 v141, v9, s21, v8 bitop3:0xde
	v_lshl_add_u64 v[8:9], v[0:1], 0, s[56:57]
	s_add_i32 m0, s25, 0x18000
	global_load_lds_dwordx4 v[8:9], off
	v_lshl_add_u64 v[8:9], v[0:1], 0, s[96:97]
	s_add_i32 m0, s25, 0x1a000
	s_add_i32 s29, s25, 0x8000
	global_load_lds_dwordx4 v[8:9], off
	v_lshl_add_u64 v[8:9], v[2:3], 0, s[56:57]
	s_mov_b32 m0, s29
	s_add_i32 s30, s25, 0xa000
	global_load_lds_dwordx4 v[8:9], off
	v_lshl_add_u64 v[2:3], v[2:3], 0, s[96:97]
	s_mov_b32 m0, s30
	s_movk_i32 s21, 0x100
	global_load_lds_dwordx4 v[2:3], off
	v_lshl_add_u64 v[2:3], v[0:1], 0, s[88:89]
	s_add_i32 m0, s25, 0x1c000
	v_lshl_add_u64 v[0:1], v[0:1], 0, s[68:69]
	global_load_lds_dwordx4 v[2:3], off
	s_add_i32 m0, s25, 0x1e000
	s_cmpk_lt_u32 s22, 0x100
	global_load_lds_dwordx4 v[0:1], off
	s_waitcnt vmcnt(8)
	s_barrier
	v_lshlrev_b32_e32 v0, 14, v6
	v_and_b32_e32 v0, 0xffff8000, v0
	s_sext_i32_i16 s51, s36
	s_waitcnt vmcnt(6)
	s_cselect_b64 s[40:41], -1, 0
	v_cmp_gt_i32_e64 s[36:37], s21, v4
	v_readlane_b32 s22, v252, 57
	s_lshl_b32 s21, s31, 8
	v_readlane_b32 s38, v252, 63
	v_lshl_add_u32 v0, v5, 11, v0
	v_and_b32_e32 v1, 1, v6
	s_add_i32 s21, s22, s21
	v_readlane_b32 s39, v253, 0
	v_lshl_or_b32 v0, v1, 6, v0
	v_lshl_add_u32 v142, v4, 2, s22
	v_add_u32_e32 v143, s21, v11
	v_lshl_add_u64 v[132:133], s[38:39], 0, v[184:185]
	v_or_b32_e32 v144, s18, v10
	v_lshl_add_u32 v184, v7, 1, v0
	s_mov_b32 s31, 0
	v_add_u32_e32 v145, 0, v12
	v_mov_b64_e32 v[134:135], s[70:71]
	s_barrier
	s_branch .LBB0_226

.LBB0_243:
	v_lshrrev_b32_e32 v9, 1, v4
	v_and_b32_e32 v8, 15, v4
	v_and_b32_e32 v10, 24, v9
	v_lshlrev_b32_e32 v9, 1, v10
	v_lshlrev_b32_e32 v11, 2, v8
	v_lshl_or_b32 v148, s22, 6, v8
	v_lshl_or_b32 v9, v8, 6, v9
	s_lshl_b32 s18, s22, 13
	v_and_b32_e32 v8, 32, v11
	v_bitop3_b32 v12, v9, s18, v8 bitop3:0xde
	s_lshl_b32 s18, s29, 5
	s_and_b32 s18, s18, 0x60
	s_lshl_b32 s21, s18, 7
	v_bitop3_b32 v149, v9, s21, v8 bitop3:0xde
	v_lshl_add_u64 v[8:9], v[0:1], 0, s[56:57]
	s_add_i32 m0, s25, 0x18000
	global_load_lds_dwordx4 v[8:9], off
	v_lshl_add_u64 v[8:9], v[0:1], 0, s[96:97]
	s_add_i32 m0, s25, 0x1a000
	s_add_i32 s29, s25, 0x8000
	global_load_lds_dwordx4 v[8:9], off
	v_lshl_add_u64 v[8:9], v[2:3], 0, s[56:57]
	s_mov_b32 m0, s29
	s_add_i32 s30, s25, 0xa000
	global_load_lds_dwordx4 v[8:9], off
	v_lshl_add_u64 v[2:3], v[2:3], 0, s[96:97]
	s_mov_b32 m0, s30
	v_or_b32_e32 v150, s18, v10
	global_load_lds_dwordx4 v[2:3], off
	v_lshl_add_u64 v[2:3], v[0:1], 0, s[88:89]
	s_add_i32 m0, s25, 0x1c000
	v_lshl_add_u64 v[0:1], v[0:1], 0, s[68:69]
	global_load_lds_dwordx4 v[2:3], off
	s_add_i32 m0, s25, 0x1e000
	s_cmpk_lt_u32 s31, 0x100
	global_load_lds_dwordx4 v[0:1], off
	s_waitcnt vmcnt(8)
	s_barrier
	v_lshlrev_b32_e32 v0, 14, v6
	s_movk_i32 s18, 0x100
	v_and_b32_e32 v0, 0xffff8000, v0
	s_sext_i32_i16 s51, s36
	s_waitcnt vmcnt(6)
	s_cselect_b64 s[40:41], -1, 0
	v_cmp_gt_i32_e64 s[36:37], s18, v4
	v_readlane_b32 s21, v252, 57
	s_lshl_b32 s18, s22, 8
	v_readlane_b32 s38, v252, 49
	v_lshl_add_u32 v0, v5, 11, v0
	v_and_b32_e32 v1, 1, v6
	s_add_i32 s18, s21, s18
	v_readlane_b32 s39, v252, 50
	v_lshl_or_b32 v0, v1, 6, v0
	v_lshl_add_u32 v151, v4, 2, s21
	v_add_u32_e32 v152, s18, v11
	v_lshl_add_u64 v[132:133], s[38:39], 0, v[184:185]
	v_lshl_add_u32 v134, v7, 1, v0
	v_mov_b32_e32 v135, v185
	s_mov_b32 s31, 0
	v_add_u32_e32 v153, 0, v12
	s_barrier
	s_branch .LBB0_246

.LBB0_303:
	s_and_b64 s[22:23], s[10:11], exec
	s_mov_b32 s17, 0xc0000
	v_readlane_b32 s44, v252, 39
	s_cselect_b32 s17, s17, 0x80000
	v_readlane_b32 s50, v252, 45
	v_readlane_b32 s45, v252, 40
	v_readlane_b32 s51, v252, 46
	s_add_u32 s44, s50, s17
	v_bfe_u32 v10, v8, 4, 2
	s_addc_u32 s45, s51, 0
	v_and_b32_e32 v9, 15, v8
	v_lshlrev_b32_e32 v11, 4, v10
	v_lshlrev_b32_e32 v8, 2, v8
	s_lshl_b32 s1, s1, 5
	v_lshl_or_b32 v220, s16, 6, v9
	v_lshl_or_b32 v9, v9, 6, v11
	s_lshl_b32 s16, s16, 13
	v_and_b32_e32 v8, 32, v8
	s_and_b32 s1, s1, 0x60
	v_bitop3_b32 v11, v9, s16, v8 bitop3:0xde
	s_lshl_b32 s16, s1, 7
	v_bitop3_b32 v221, v9, s16, v8 bitop3:0xde
	v_lshl_add_u64 v[8:9], v[0:1], 0, s[56:57]
	s_add_i32 m0, s19, 0x18000
	global_load_lds_dwordx4 v[8:9], off
	v_lshl_add_u64 v[8:9], v[0:1], 0, s[82:83]
	s_add_i32 m0, s19, 0x1a000
	s_add_i32 s28, s19, 0x8000
	global_load_lds_dwordx4 v[8:9], off
	v_lshl_add_u64 v[8:9], v[2:3], 0, s[56:57]
	s_mov_b32 m0, s28
	s_add_i32 s29, s19, 0xa000
	global_load_lds_dwordx4 v[8:9], off
	v_lshl_add_u64 v[2:3], v[2:3], 0, s[82:83]
	s_mov_b32 m0, s29
	v_lshl_or_b32 v222, v10, 3, s1
	global_load_lds_dwordx4 v[2:3], off
	v_lshl_add_u64 v[2:3], v[0:1], 0, s[80:81]
	s_add_i32 m0, s19, 0x1c000
	v_lshl_add_u64 v[0:1], v[0:1], 0, s[74:75]
	global_load_lds_dwordx4 v[2:3], off
	s_add_i32 m0, s19, 0x1e000
	s_cmpk_lt_u32 s0, 0x100
	global_load_lds_dwordx4 v[0:1], off
	s_waitcnt vmcnt(8)
	s_barrier
	v_lshrrev_b32_e32 v1, 1, v5
	v_mul_lo_u32 v0, v4, s18
	s_movk_i32 s0, 0x5800
	s_waitcnt vmcnt(6)
	v_mad_u64_u32 v[0:1], s[0:1], v1, s0, v[0:1]
	v_readlane_b32 s46, v252, 41
	v_readlane_b32 s47, v252, 42
	v_or_b32_e32 v0, v0, v6
	v_readlane_b32 s16, v254, 38
	s_mov_b32 s27, 0
	s_cselect_b64 s[46:47], -1, 0
	v_cmp_eq_u32_e64 s[36:37], 0, v10
	v_add_lshl_u32 v196, v0, v7, 1
	v_mov_b32_e32 v197, v185
	v_add_u32_e32 v223, 0, v11
	v_readlane_b32 s60, v254, 34
	v_readlane_b32 s61, v254, 37
	v_readlane_b32 s17, v254, 39
	s_mov_b32 s18, 0x44800000
	v_readlane_b32 s48, v252, 43
	v_readlane_b32 s49, v252, 44
	s_barrier
	s_branch .LBB0_306

.LBB0_348:
	v_readlane_b32 s12, v254, 49
	v_readlane_b32 s72, v252, 1
	s_cmp_eq_u32 s12, 1
	v_readlane_b32 s73, v252, 2
	v_readlane_b32 s74, v252, 3
	v_readlane_b32 s75, v252, 4
	s_cselect_b32 s75, s73, 0
	s_cselect_b32 s74, s72, 0
	s_and_b64 s[10:11], s[10:11], exec
	s_mov_b32 s10, 0x60000
	s_cselect_b32 s10, s10, 0x20000
	s_and_b64 s[8:9], s[8:9], exec
	v_readlane_b32 s60, v252, 39
	s_cselect_b32 s8, 0x40000, s10
	v_readlane_b32 s66, v252, 45
	v_readlane_b32 s67, v252, 46
	s_add_u32 s36, s66, s8
	s_addc_u32 s37, s67, 0
	v_lshl_add_u64 v[4:5], v[4:5], 0, s[56:57]
	s_add_i32 m0, s28, 0x18000
	global_load_lds_dwordx4 v[4:5], off
	v_lshl_add_u64 v[4:5], v[6:7], 0, s[56:57]
	s_add_i32 m0, s28, 0x1a000
	s_add_i32 s19, s28, 0x8000
	global_load_lds_dwordx4 v[4:5], off
	v_lshl_add_u64 v[4:5], v[10:11], 0, s[56:57]
	s_mov_b32 m0, s19
	s_add_i32 s20, s28, 0xa000
	global_load_lds_dwordx4 v[4:5], off
	v_lshl_add_u64 v[4:5], v[8:9], 0, s[56:57]
	s_mov_b32 m0, s20
	v_lshl_add_u64 v[0:1], v[0:1], 0, s[56:57]
	global_load_lds_dwordx4 v[4:5], off
	s_add_i32 m0, s28, 0x1c000
	v_bfe_u32 v17, v15, 4, 2
	global_load_lds_dwordx4 v[0:1], off
	v_lshl_add_u64 v[0:1], v[2:3], 0, s[56:57]
	s_add_i32 m0, s28, 0x1e000
	v_and_b32_e32 v16, 15, v15
	global_load_lds_dwordx4 v[0:1], off
	s_waitcnt vmcnt(8)
	s_barrier
	v_lshlrev_b32_e32 v18, 4, v17
	v_lshlrev_b32_e32 v15, 2, v15
	s_lshl_b32 s1, s1, 5
	v_readlane_b32 s84, v252, 13
	v_readlane_b32 s12, v254, 63
	v_lshl_or_b32 v222, s6, 6, v16
	v_lshl_or_b32 v16, v16, 6, v18
	s_lshl_b32 s6, s6, 13
	v_and_b32_e32 v15, 32, v15
	s_and_b32 s1, s1, 0x60
	s_lshr_b32 s84, s12, 6
	v_bitop3_b32 v18, v16, s6, v15 bitop3:0xde
	s_lshl_b32 s6, s1, 7
	v_bitop3_b32 v223, v16, s6, v15 bitop3:0xde
	s_add_i32 s6, s84, -2
	v_readlane_b32 s78, v252, 7
	v_readlane_b32 s79, v252, 8
	v_readlane_b32 s61, v252, 40
	s_waitcnt vmcnt(6)
	s_cmpk_lt_u32 s0, 0x100
	v_add_u32_e32 v0, v14, v12
	v_readlane_b32 s76, v252, 5
	v_readlane_b32 s77, v252, 6
	v_readlane_b32 s80, v252, 9
	v_readlane_b32 s81, v252, 10
	v_readlane_b32 s82, v252, 11
	v_readlane_b32 s83, v252, 12
	v_readlane_b32 s85, v252, 14
	v_readlane_b32 s86, v252, 15
	v_readlane_b32 s87, v252, 16
	v_readlane_b32 s62, v252, 41
	v_readlane_b32 s63, v252, 42
	v_readlane_b32 s64, v252, 43
	v_readlane_b32 s65, v252, 44
	s_cselect_b64 s[60:61], -1, 0
	s_cmp_lg_u64 s[74:75], 0
	v_add_lshl_u32 v0, v0, v13, 1
	v_mov_b32_e32 v1, v185
	v_readlane_b32 s72, v254, 56
	v_readlane_b32 s78, v254, 54
	s_mov_b32 s43, s42
	s_mov_b32 s48, s42
	s_mov_b32 s49, s42
	s_mov_b32 s25, 0
	v_cmp_eq_u32_e64 s[8:9], 0, v17
	s_cselect_b64 s[10:11], -1, 0
	v_lshl_or_b32 v224, v17, 3, s1
	v_lshl_add_u64 v[196:197], s[44:45], 0, v[0:1]
	v_mad_u64_u32 v[198:199], s[0:1], s12, v247, v[0:1]
	v_add_u32_e32 v225, 0, v18
	v_readlane_b32 s45, v254, 34
	v_readlane_b32 s85, v254, 37
	s_mov_b64 s[62:63], s[38:39]
	v_readlane_b32 s87, v252, 0
	s_mov_b32 s76, s24
	s_mov_b64 s[64:65], s[46:47]
	s_mov_b64 s[66:67], vcc
	v_readlane_b32 s73, v254, 57
	v_readlane_b32 s77, v254, 53
	v_readlane_b32 s79, v254, 55
	s_movk_i32 s86, 0x161
	s_mov_b64 s[82:83], 0x2c080
	s_mov_b64 s[80:81], 0x58080
	s_barrier
	s_branch .LBB0_351

.LBB0_408:
	v_lshl_add_u64 v[4:5], v[4:5], 0, s[56:57]
	s_add_i32 m0, s20, 0x18000
	global_load_lds_dwordx4 v[4:5], off
	v_lshl_add_u64 v[4:5], v[6:7], 0, s[56:57]
	s_add_i32 m0, s20, 0x1a000
	s_add_i32 s29, s20, 0x8000
	global_load_lds_dwordx4 v[4:5], off
	v_lshl_add_u64 v[4:5], v[10:11], 0, s[56:57]
	s_mov_b32 m0, s29
	s_add_i32 s30, s20, 0xa000
	global_load_lds_dwordx4 v[4:5], off
	v_lshl_add_u64 v[4:5], v[8:9], 0, s[56:57]
	s_mov_b32 m0, s30
	v_lshl_add_u64 v[0:1], v[0:1], 0, s[56:57]
	global_load_lds_dwordx4 v[4:5], off
	s_add_i32 m0, s20, 0x1c000
	v_bfe_u32 v17, v15, 4, 2
	global_load_lds_dwordx4 v[0:1], off
	v_lshl_add_u64 v[0:1], v[2:3], 0, s[56:57]
	s_add_i32 m0, s20, 0x1e000
	v_and_b32_e32 v16, 15, v15
	global_load_lds_dwordx4 v[0:1], off
	s_waitcnt vmcnt(8)
	s_barrier
	v_lshlrev_b32_e32 v18, 4, v17
	v_lshlrev_b32_e32 v15, 2, v15
	s_lshl_b32 s1, s1, 5
	s_lshr_b32 s28, s23, 6
	v_lshl_or_b32 v248, s12, 6, v16
	v_lshl_or_b32 v16, v16, 6, v18
	s_lshl_b32 s12, s12, 13
	v_and_b32_e32 v15, 32, v15
	s_and_b32 s1, s1, 0x60
	v_bitop3_b32 v18, v16, s12, v15 bitop3:0xde
	s_lshl_b32 s12, s1, 7
	s_waitcnt vmcnt(6)
	s_add_i32 s31, s28, -2
	v_add_u32_e32 v0, v14, v12
	s_cmpk_lt_u32 s0, 0x100
	v_add_lshl_u32 v0, v0, v13, 1
	v_mov_b32_e32 v1, v185
	v_bitop3_b32 v249, v16, s12, v15 bitop3:0xde
	s_cselect_b64 s[12:13], -1, 0
	s_mov_b32 s46, 0
	v_cmp_eq_u32_e64 s[36:37], 0, v17
	v_lshl_or_b32 v250, v17, 3, s1
	v_lshl_add_u64 v[196:197], s[8:9], 0, v[0:1]
	v_mad_u64_u32 v[198:199], s[0:1], s23, v247, v[0:1]
	v_add_u32_e32 v251, 0, v18
	v_readlane_b32 s48, v254, 34
	v_readlane_b32 s22, v254, 37
	s_mov_b32 s18, 0x44800000
	s_mov_b32 s21, 0x13000000
	s_barrier
	s_branch .LBB0_411

.LBB0_453:
	v_lshrrev_b32_e32 v10, 1, v6
	v_and_b32_e32 v12, 24, v10
	v_and_b32_e32 v1, 15, v6
	v_lshlrev_b32_e32 v10, 1, v12
	v_lshl_or_b32 v141, s16, 6, v1
	v_lshl_or_b32 v10, v1, 6, v10
	v_lshlrev_b32_e32 v1, 2, v1
	s_lshl_b32 s17, s16, 13
	v_and_b32_e32 v11, 32, v1
	s_lshl_b32 s11, s11, 5
	v_bitop3_b32 v13, v10, s17, v11 bitop3:0xde
	s_and_b32 s17, s11, 0x60
	s_lshl_b32 s11, s17, 7
	v_bitop3_b32 v142, v10, s11, v11 bitop3:0xde
	v_lshl_add_u64 v[10:11], v[2:3], 0, s[56:57]
	s_add_i32 m0, s19, 0x18000
	global_load_lds_dwordx4 v[10:11], off
	v_lshl_add_u64 v[10:11], v[2:3], 0, s[96:97]
	s_add_i32 m0, s19, 0x1a000
	s_add_i32 s26, s19, 0x8000
	global_load_lds_dwordx4 v[10:11], off
	v_lshl_add_u64 v[10:11], v[4:5], 0, s[56:57]
	s_mov_b32 m0, s26
	s_add_i32 s27, s19, 0xa000
	global_load_lds_dwordx4 v[10:11], off
	v_lshl_add_u64 v[4:5], v[4:5], 0, s[96:97]
	s_mov_b32 m0, s27
	s_movk_i32 s18, 0x100
	global_load_lds_dwordx4 v[4:5], off
	v_lshl_add_u64 v[4:5], v[2:3], 0, s[88:89]
	s_add_i32 m0, s19, 0x1c000
	v_lshl_add_u64 v[2:3], v[2:3], 0, s[68:69]
	global_load_lds_dwordx4 v[4:5], off
	s_add_i32 m0, s19, 0x1e000
	s_cmpk_lt_u32 s10, 0x100
	global_load_lds_dwordx4 v[2:3], off
	s_waitcnt vmcnt(8)
	s_barrier
	s_cselect_b64 s[10:11], -1, 0
	v_cmp_gt_i32_e64 s[38:39], s18, v6
	v_readlane_b32 s18, v252, 57
	s_lshl_b32 s16, s16, 8
	s_add_i32 s16, s18, s16
	v_add_u32_e32 v144, s16, v1
	v_mov_b32_e32 v1, v185
	v_lshl_add_u64 v[130:131], s[12:13], 0, v[0:1]
	v_lshlrev_b32_e32 v0, 14, v7
	v_and_b32_e32 v0, 0xffff8000, v0
	s_waitcnt vmcnt(6)
	v_lshl_add_u32 v0, v8, 11, v0
	v_and_b32_e32 v1, 1, v7
	v_or_b32_e32 v145, s17, v12
	v_lshl_or_b32 v0, v1, 6, v0
	v_readlane_b32 s12, v254, 26
	v_readlane_b32 s16, v254, 22
	v_lshl_add_u32 v143, v6, 2, s18
	v_lshl_add_u32 v132, v9, 1, v0
	v_mov_b32_e32 v133, v185
	s_mov_b32 s28, 0
	v_add_u32_e32 v146, 0, v13
	v_readlane_b32 s29, v254, 17
	s_mov_b32 s30, s12
	v_readlane_b32 s17, v254, 23
	s_movk_i32 s18, 0x1600
	s_barrier
	v_readlane_b32 s13, v254, 27
	s_branch .LBB0_456

.LBB0_475:
	v_lshrrev_b32_e32 v9, 1, v4
	v_and_b32_e32 v8, 15, v4
	v_and_b32_e32 v10, 24, v9
	v_lshlrev_b32_e32 v9, 1, v10
	v_lshlrev_b32_e32 v11, 2, v8
	v_lshl_or_b32 v142, s16, 6, v8
	v_lshl_or_b32 v9, v8, 6, v9
	s_lshl_b32 s17, s16, 13
	v_and_b32_e32 v8, 32, v11
	s_lshl_b32 s11, s11, 5
	v_bitop3_b32 v12, v9, s17, v8 bitop3:0xde
	s_and_b32 s17, s11, 0x60
	s_lshl_b32 s11, s17, 7
	v_bitop3_b32 v143, v9, s11, v8 bitop3:0xde
	v_lshl_add_u64 v[8:9], v[0:1], 0, s[56:57]
	s_add_i32 m0, s19, 0x18000
	global_load_lds_dwordx4 v[8:9], off
	v_lshl_add_u64 v[8:9], v[0:1], 0, s[96:97]
	s_add_i32 m0, s19, 0x1a000
	s_add_i32 s26, s19, 0x8000
	global_load_lds_dwordx4 v[8:9], off
	v_lshl_add_u64 v[8:9], v[2:3], 0, s[56:57]
	s_mov_b32 m0, s26
	s_add_i32 s27, s19, 0xa000
	global_load_lds_dwordx4 v[8:9], off
	v_lshl_add_u64 v[2:3], v[2:3], 0, s[96:97]
	s_mov_b32 m0, s27
	s_movk_i32 s18, 0x100
	global_load_lds_dwordx4 v[2:3], off
	v_lshl_add_u64 v[2:3], v[0:1], 0, s[88:89]
	s_add_i32 m0, s19, 0x1c000
	v_lshl_add_u64 v[0:1], v[0:1], 0, s[68:69]
	global_load_lds_dwordx4 v[2:3], off
	s_add_i32 m0, s19, 0x1e000
	s_cmpk_lt_u32 s10, 0x100
	global_load_lds_dwordx4 v[0:1], off
	s_waitcnt vmcnt(8)
	s_barrier
	v_lshlrev_b32_e32 v0, 14, v6
	s_cselect_b64 s[10:11], -1, 0
	v_cmp_gt_i32_e64 s[36:37], s18, v4
	v_readlane_b32 s18, v252, 57
	s_lshl_b32 s16, s16, 8
	v_and_b32_e32 v0, 0xffff8000, v0
	s_waitcnt vmcnt(6)
	s_add_i32 s16, s18, s16
	v_lshl_add_u32 v0, v5, 11, v0
	v_and_b32_e32 v1, 1, v6
	v_add_u32_e32 v145, s16, v11
	v_lshl_add_u64 v[132:133], s[12:13], 0, v[184:185]
	v_or_b32_e32 v146, s17, v10
	v_lshl_or_b32 v0, v1, 6, v0
	v_readlane_b32 s12, v254, 26
	v_readlane_b32 s16, v254, 22
	v_lshl_add_u32 v144, v4, 2, s18
	v_lshl_add_u32 v184, v7, 1, v0
	s_mov_b32 s28, 0
	v_add_u32_e32 v147, 0, v12
	v_readlane_b32 s29, v254, 17
	s_mov_b32 s30, s12
	v_readlane_b32 s17, v254, 23
	s_movk_i32 s18, 0xb00
	s_barrier
	v_readlane_b32 s13, v254, 27
	s_branch .LBB0_478

.LBB0_497:
	v_lshrrev_b32_e32 v10, 1, v6
	v_and_b32_e32 v12, 24, v10
	v_and_b32_e32 v1, 15, v6
	v_lshlrev_b32_e32 v10, 1, v12
	v_lshl_or_b32 v171, s12, 6, v1
	v_lshl_or_b32 v10, v1, 6, v10
	v_lshlrev_b32_e32 v1, 2, v1
	s_lshl_b32 s13, s12, 13
	v_and_b32_e32 v11, 32, v1
	s_lshl_b32 s9, s9, 5
	v_bitop3_b32 v13, v10, s13, v11 bitop3:0xde
	s_and_b32 s13, s9, 0x60
	s_lshl_b32 s9, s13, 7
	v_bitop3_b32 v172, v10, s9, v11 bitop3:0xde
	v_lshl_add_u64 v[10:11], v[2:3], 0, s[56:57]
	s_add_i32 m0, s19, 0x18000
	global_load_lds_dwordx4 v[10:11], off
	v_lshl_add_u64 v[10:11], v[2:3], 0, s[58:59]
	s_add_i32 m0, s19, 0x1a000
	s_add_i32 s26, s19, 0x8000
	global_load_lds_dwordx4 v[10:11], off
	v_lshl_add_u64 v[10:11], v[4:5], 0, s[56:57]
	s_mov_b32 m0, s26
	s_add_i32 s27, s19, 0xa000
	global_load_lds_dwordx4 v[10:11], off
	v_lshl_add_u64 v[4:5], v[4:5], 0, s[58:59]
	s_mov_b32 m0, s27
	s_movk_i32 s16, 0x100
	global_load_lds_dwordx4 v[4:5], off
	v_lshl_add_u64 v[4:5], v[2:3], 0, s[96:97]
	s_add_i32 m0, s19, 0x1c000
	v_lshl_add_u64 v[2:3], v[2:3], 0, s[4:5]
	global_load_lds_dwordx4 v[4:5], off
	s_add_i32 m0, s19, 0x1e000
	s_cmpk_lt_u32 s8, 0x100
	global_load_lds_dwordx4 v[2:3], off
	s_waitcnt vmcnt(8)
	s_barrier
	s_cselect_b64 s[8:9], -1, 0
	v_cmp_gt_i32_e64 s[38:39], s16, v6
	v_readlane_b32 s16, v252, 57
	s_lshl_b32 s12, s12, 8
	s_add_i32 s12, s16, s12
	v_add_u32_e32 v174, s12, v1
	v_mov_b32_e32 v1, v185
	v_lshl_add_u64 v[162:163], s[10:11], 0, v[0:1]
	v_lshlrev_b32_e32 v0, 13, v7
	v_and_b32_e32 v0, 0xffffc000, v0
	s_waitcnt vmcnt(6)
	v_lshl_add_u32 v0, v8, 10, v0
	v_and_b32_e32 v1, 1, v7
	v_lshl_add_u32 v173, v6, 2, s16
	v_lshl_or_b32 v0, v1, 6, v0
	v_readlane_b32 s10, v254, 26
	v_readlane_b32 s16, v254, 30
	v_or_b32_e32 v175, s13, v12
	v_lshl_add_u32 v164, v9, 1, v0
	v_mov_b32_e32 v165, v185
	s_mov_b32 s28, 0
	v_add_u32_e32 v176, 0, v13
	v_readlane_b32 s29, v254, 17
	s_mov_b32 s30, s10
	v_readlane_b32 s17, v254, 31
	s_barrier
	v_readlane_b32 s11, v254, 27
	s_branch .LBB0_500
